# chunk boundary: barrier and next-chunk operand loads issued ahead of the y reduction
# baseline (speedup 1.0000x reference)
.LBB0_679:
	s_lshl_b32 s6, s25, 2
	s_and_b32 s6, s6, 28
	s_ashr_i32 s7, s25, 6
	v_readlane_b32 s8, v253, 44
	s_add_i32 s6, s6, s7
	v_readlane_b32 s9, v253, 45
	s_ashr_i32 s26, s6, 3
	s_and_b32 s27, s6, 7
	s_mov_b64 s[6:7], -1
	s_and_b64 vcc, exec, s[8:9]
	s_cbranch_vccz .LBB0_694
	s_and_b32 s6, s25, 56
	v_add_u32_e32 v46, s6, v57
	s_lshr_b32 s6, s25, 6
	s_and_b32 s7, s24, 4
	s_add_i32 s7, s7, s6
	s_and_b32 s6, s7, 7
	s_mul_i32 s29, s26, 0x808000
	s_lshl_b32 s6, s6, 8
	s_mul_hi_i32 s28, s26, 0x808000
	s_or_b32 s6, s29, s6
	v_ashrrev_i32_e32 v47, 31, v46
	s_waitcnt lgkmcnt(0)
	s_barrier
	v_mov_b32_e32 v0, s6
	v_mov_b32_e32 v1, s28
	v_lshl_add_u64 v[0:1], v[46:47], 2, v[0:1]
	v_mov_b32_e32 v162, v163
	v_lshlrev_b32_e32 v86, 2, v46
	v_lshl_add_u64 v[48:49], v[44:45], 0, v[0:1]
	v_lshl_add_u64 v[50:51], s[90:91], 0, v[0:1]
	s_mov_b32 s30, 0
	s_mov_b64 s[88:89], 0
	s_movk_i32 s31, 0x1010
	v_mov_b64_e32 v[52:53], v[162:163]
	v_lshrrev_b32_e32 v2, 1, v57
	v_and_b32_e32 v3, 1, v57
	v_mul_u32_u24_e32 v2, 0x1200, v2
	v_lshl_add_u32 v2, v3, 6, v2
	v_add_u32_e32 v2, 0x1c000, v2
	v_mbcnt_lo_u32_b32 v3, -1, 0
	v_mbcnt_hi_u32_b32 v3, -1, v3
	v_and_b32_e32 v87, 31, v3
	v_lshrrev_b32_e32 v3, 1, v87
	v_lshl_add_u32 v91, v3, 2, v2
	v_mul_u32_u24_e32 v3, 0x90, v87
	v_add_u32_e32 v92, v3, v2
	v_lshlrev_b32_e32 v94, 11, v87
	v_mov_b32_e32 v95, 0
	s_branch .LBB0_682
.LBB0_682:
	s_bitcmp1_b32 s30, 0
	s_cselect_b32 s6, 0xe000, 0
	s_add_i32 s6, s6, 0
	v_add_u32_e32 v90, s6, v58
	v_sub_u32_e32 v88, v90, v61
	v_add_u32_e32 v89, s6, v86
	ds_read_b128 v[4:7], v90 offset:0x4000
	ds_read_b128 v[8:11], v90 offset:0x0
	ds_read2st64_b32 v[108:109], v89 offset0:192 offset1:193
	ds_read2st64_b64 v[100:103], v88 offset0:64 offset1:65
	ds_read_b128 v[112:115], v90 offset:0x4200
	ds_read_b128 v[96:99], v90 offset:0x200
	v_mov_b32_e32 v93, v91
	s_waitcnt lgkmcnt(3)
.Lrw_steps:
	v_pk_mul_f32 v[0:1], v[52:53], v[4:5] op_sel_hi:[0,1]
	v_pk_fma_f32 v[0:1], v[52:53], v[6:7], v[0:1] op_sel:[1,0,0]
	v_pk_mul_f32 v[10:11], v[108:109], v[10:11] op_sel_hi:[0,1]
	ds_read_b128 v[4:7], v90 offset:0x4400
	v_add_f32_dpp v0, v0, v0 quad_perm:[1,0,3,2] row_mask:0xf bank_mask:0xf bound_ctrl:1
	v_add_f32_dpp v1, v1, v1 quad_perm:[1,0,3,2] row_mask:0xf bank_mask:0xf bound_ctrl:1
	v_pk_fma_f32 v[54:55], v[52:53], v[8:9], v[10:11]
	v_add_f32_dpp v0, v0, v0 quad_perm:[2,3,0,1] row_mask:0xf bank_mask:0xf bound_ctrl:1
	ds_read_b128 v[8:11], v90 offset:0x400
	s_nop 0
	v_add_f32_dpp v0, v0, v0 row_half_mirror row_mask:0xf bank_mask:0xf bound_ctrl:1
	s_nop 0
	s_nop 0
	v_add_f32_dpp v2, v0, v0 row_mirror row_mask:0xf bank_mask:0xf bound_ctrl:1
	v_add_f32_dpp v0, v0, v0 row_mirror row_mask:0xf bank_mask:0xf bound_ctrl:1
	ds_read2st64_b32 v[110:111], v89 offset0:194 offset1:195
	s_waitcnt lgkmcnt(3)
	v_permlane16_swap_b32_e32 v0, v2
	v_add_f32_e32 v0, v0, v2
	v_pk_fma_f32 v[52:53], v[100:101], v[0:1], v[54:55] op_sel_hi:[1,0,1]
	v_pk_mul_f32 v[118:119], v[52:53], v[112:113] op_sel_hi:[0,1]
	v_pk_fma_f32 v[118:119], v[52:53], v[114:115], v[118:119] op_sel:[1,0,0]
	v_pk_mul_f32 v[98:99], v[108:109], v[98:99] op_sel:[1,0]
	ds_read_b128 v[112:115], v90 offset:0x4600
	v_add_f32_dpp v118, v118, v118 quad_perm:[1,0,3,2] row_mask:0xf bank_mask:0xf bound_ctrl:1
	v_add_f32_dpp v119, v119, v119 quad_perm:[1,0,3,2] row_mask:0xf bank_mask:0xf bound_ctrl:1
	v_pk_fma_f32 v[54:55], v[52:53], v[96:97], v[98:99]
	v_add_f32_dpp v118, v118, v118 quad_perm:[2,3,0,1] row_mask:0xf bank_mask:0xf bound_ctrl:1
	ds_read_b128 v[96:99], v90 offset:0x600
	s_nop 0
	v_add_f32_dpp v118, v118, v118 row_half_mirror row_mask:0xf bank_mask:0xf bound_ctrl:1
	ds_write2_b32 v93, v1, v119 offset0:0 offset1:36
	s_nop 0
	v_add_f32_dpp v2, v118, v118 row_mirror row_mask:0xf bank_mask:0xf bound_ctrl:1
	v_add_f32_dpp v118, v118, v118 row_mirror row_mask:0xf bank_mask:0xf bound_ctrl:1
	ds_read2st64_b64 v[104:107], v88 offset0:66 offset1:67
	s_waitcnt lgkmcnt(4)
	v_permlane16_swap_b32_e32 v118, v2
	v_add_f32_e32 v118, v118, v2
	v_pk_fma_f32 v[52:53], v[102:103], v[118:119], v[54:55] op_sel_hi:[1,0,1]
	v_pk_mul_f32 v[0:1], v[52:53], v[4:5] op_sel_hi:[0,1]
	v_pk_fma_f32 v[0:1], v[52:53], v[6:7], v[0:1] op_sel:[1,0,0]
	v_pk_mul_f32 v[10:11], v[110:111], v[10:11] op_sel_hi:[0,1]
	ds_read_b128 v[4:7], v90 offset:0x4800
	v_add_f32_dpp v0, v0, v0 quad_perm:[1,0,3,2] row_mask:0xf bank_mask:0xf bound_ctrl:1
	v_add_f32_dpp v1, v1, v1 quad_perm:[1,0,3,2] row_mask:0xf bank_mask:0xf bound_ctrl:1
	v_pk_fma_f32 v[54:55], v[52:53], v[8:9], v[10:11]
	v_add_f32_dpp v0, v0, v0 quad_perm:[2,3,0,1] row_mask:0xf bank_mask:0xf bound_ctrl:1
	ds_read_b128 v[8:11], v90 offset:0x800
	s_nop 0
	v_add_f32_dpp v0, v0, v0 row_half_mirror row_mask:0xf bank_mask:0xf bound_ctrl:1
	s_nop 0
	s_nop 0
	v_add_f32_dpp v2, v0, v0 row_mirror row_mask:0xf bank_mask:0xf bound_ctrl:1
	v_add_f32_dpp v0, v0, v0 row_mirror row_mask:0xf bank_mask:0xf bound_ctrl:1
	ds_read2st64_b32 v[108:109], v89 offset0:196 offset1:197
	s_waitcnt lgkmcnt(3)
	v_permlane16_swap_b32_e32 v0, v2
	v_add_f32_e32 v0, v0, v2
	v_pk_fma_f32 v[52:53], v[104:105], v[0:1], v[54:55] op_sel_hi:[1,0,1]
	v_pk_mul_f32 v[118:119], v[52:53], v[112:113] op_sel_hi:[0,1]
	v_pk_fma_f32 v[118:119], v[52:53], v[114:115], v[118:119] op_sel:[1,0,0]
	v_pk_mul_f32 v[98:99], v[110:111], v[98:99] op_sel:[1,0]
	ds_read_b128 v[112:115], v90 offset:0x4a00
	v_add_f32_dpp v118, v118, v118 quad_perm:[1,0,3,2] row_mask:0xf bank_mask:0xf bound_ctrl:1
	v_add_f32_dpp v119, v119, v119 quad_perm:[1,0,3,2] row_mask:0xf bank_mask:0xf bound_ctrl:1
	v_pk_fma_f32 v[54:55], v[52:53], v[96:97], v[98:99]
	v_add_f32_dpp v118, v118, v118 quad_perm:[2,3,0,1] row_mask:0xf bank_mask:0xf bound_ctrl:1
	ds_read_b128 v[96:99], v90 offset:0xa00
	s_nop 0
	v_add_f32_dpp v118, v118, v118 row_half_mirror row_mask:0xf bank_mask:0xf bound_ctrl:1
	ds_write2_b32 v93, v1, v119 offset0:72 offset1:108
	s_nop 0
	v_add_f32_dpp v2, v118, v118 row_mirror row_mask:0xf bank_mask:0xf bound_ctrl:1
	v_add_f32_dpp v118, v118, v118 row_mirror row_mask:0xf bank_mask:0xf bound_ctrl:1
	ds_read2st64_b64 v[100:103], v88 offset0:68 offset1:69
	s_waitcnt lgkmcnt(4)
	v_permlane16_swap_b32_e32 v118, v2
	v_add_f32_e32 v118, v118, v2
	v_pk_fma_f32 v[52:53], v[106:107], v[118:119], v[54:55] op_sel_hi:[1,0,1]
	v_pk_mul_f32 v[0:1], v[52:53], v[4:5] op_sel_hi:[0,1]
	v_pk_fma_f32 v[0:1], v[52:53], v[6:7], v[0:1] op_sel:[1,0,0]
	v_pk_mul_f32 v[10:11], v[108:109], v[10:11] op_sel_hi:[0,1]
	ds_read_b128 v[4:7], v90 offset:0x4c00
	v_add_f32_dpp v0, v0, v0 quad_perm:[1,0,3,2] row_mask:0xf bank_mask:0xf bound_ctrl:1
	v_add_f32_dpp v1, v1, v1 quad_perm:[1,0,3,2] row_mask:0xf bank_mask:0xf bound_ctrl:1
	v_pk_fma_f32 v[54:55], v[52:53], v[8:9], v[10:11]
	v_add_f32_dpp v0, v0, v0 quad_perm:[2,3,0,1] row_mask:0xf bank_mask:0xf bound_ctrl:1
	ds_read_b128 v[8:11], v90 offset:0xc00
	s_nop 0
	v_add_f32_dpp v0, v0, v0 row_half_mirror row_mask:0xf bank_mask:0xf bound_ctrl:1
	s_nop 0
	s_nop 0
	v_add_f32_dpp v2, v0, v0 row_mirror row_mask:0xf bank_mask:0xf bound_ctrl:1
	v_add_f32_dpp v0, v0, v0 row_mirror row_mask:0xf bank_mask:0xf bound_ctrl:1
	ds_read2st64_b32 v[110:111], v89 offset0:198 offset1:199
	s_waitcnt lgkmcnt(3)
	v_permlane16_swap_b32_e32 v0, v2
	v_add_f32_e32 v0, v0, v2
	v_pk_fma_f32 v[52:53], v[100:101], v[0:1], v[54:55] op_sel_hi:[1,0,1]
	v_pk_mul_f32 v[118:119], v[52:53], v[112:113] op_sel_hi:[0,1]
	v_pk_fma_f32 v[118:119], v[52:53], v[114:115], v[118:119] op_sel:[1,0,0]
	v_pk_mul_f32 v[98:99], v[108:109], v[98:99] op_sel:[1,0]
	ds_read_b128 v[112:115], v90 offset:0x4e00
	v_add_f32_dpp v118, v118, v118 quad_perm:[1,0,3,2] row_mask:0xf bank_mask:0xf bound_ctrl:1
	v_add_f32_dpp v119, v119, v119 quad_perm:[1,0,3,2] row_mask:0xf bank_mask:0xf bound_ctrl:1
	v_pk_fma_f32 v[54:55], v[52:53], v[96:97], v[98:99]
	v_add_f32_dpp v118, v118, v118 quad_perm:[2,3,0,1] row_mask:0xf bank_mask:0xf bound_ctrl:1
	ds_read_b128 v[96:99], v90 offset:0xe00
	s_nop 0
	v_add_f32_dpp v118, v118, v118 row_half_mirror row_mask:0xf bank_mask:0xf bound_ctrl:1
	ds_write2_b32 v93, v1, v119 offset0:144 offset1:180
	s_nop 0
	v_add_f32_dpp v2, v118, v118 row_mirror row_mask:0xf bank_mask:0xf bound_ctrl:1
	v_add_f32_dpp v118, v118, v118 row_mirror row_mask:0xf bank_mask:0xf bound_ctrl:1
	ds_read2st64_b64 v[104:107], v88 offset0:70 offset1:71
	s_waitcnt lgkmcnt(4)
	v_permlane16_swap_b32_e32 v118, v2
	v_add_f32_e32 v118, v118, v2
	v_pk_fma_f32 v[52:53], v[102:103], v[118:119], v[54:55] op_sel_hi:[1,0,1]
	v_pk_mul_f32 v[0:1], v[52:53], v[4:5] op_sel_hi:[0,1]
	v_pk_fma_f32 v[0:1], v[52:53], v[6:7], v[0:1] op_sel:[1,0,0]
	v_pk_mul_f32 v[10:11], v[110:111], v[10:11] op_sel_hi:[0,1]
	ds_read_b128 v[4:7], v90 offset:0x5000
	v_add_f32_dpp v0, v0, v0 quad_perm:[1,0,3,2] row_mask:0xf bank_mask:0xf bound_ctrl:1
	v_add_f32_dpp v1, v1, v1 quad_perm:[1,0,3,2] row_mask:0xf bank_mask:0xf bound_ctrl:1
	v_pk_fma_f32 v[54:55], v[52:53], v[8:9], v[10:11]
	v_add_f32_dpp v0, v0, v0 quad_perm:[2,3,0,1] row_mask:0xf bank_mask:0xf bound_ctrl:1
	ds_read_b128 v[8:11], v90 offset:0x1000
	s_nop 0
	v_add_f32_dpp v0, v0, v0 row_half_mirror row_mask:0xf bank_mask:0xf bound_ctrl:1
	s_nop 0
	s_nop 0
	v_add_f32_dpp v2, v0, v0 row_mirror row_mask:0xf bank_mask:0xf bound_ctrl:1
	v_add_f32_dpp v0, v0, v0 row_mirror row_mask:0xf bank_mask:0xf bound_ctrl:1
	ds_read2st64_b32 v[108:109], v89 offset0:200 offset1:201
	s_waitcnt lgkmcnt(3)
	v_permlane16_swap_b32_e32 v0, v2
	v_add_f32_e32 v0, v0, v2
	v_pk_fma_f32 v[52:53], v[104:105], v[0:1], v[54:55] op_sel_hi:[1,0,1]
	v_pk_mul_f32 v[118:119], v[52:53], v[112:113] op_sel_hi:[0,1]
	v_pk_fma_f32 v[118:119], v[52:53], v[114:115], v[118:119] op_sel:[1,0,0]
	v_pk_mul_f32 v[98:99], v[110:111], v[98:99] op_sel:[1,0]
	ds_read_b128 v[112:115], v90 offset:0x5200
	v_add_f32_dpp v118, v118, v118 quad_perm:[1,0,3,2] row_mask:0xf bank_mask:0xf bound_ctrl:1
	v_add_f32_dpp v119, v119, v119 quad_perm:[1,0,3,2] row_mask:0xf bank_mask:0xf bound_ctrl:1
	v_pk_fma_f32 v[54:55], v[52:53], v[96:97], v[98:99]
	v_add_f32_dpp v118, v118, v118 quad_perm:[2,3,0,1] row_mask:0xf bank_mask:0xf bound_ctrl:1
	ds_read_b128 v[96:99], v90 offset:0x1200
	s_nop 0
	v_add_f32_dpp v118, v118, v118 row_half_mirror row_mask:0xf bank_mask:0xf bound_ctrl:1
	ds_write2_b32 v93, v1, v119 offset0:216 offset1:252
	s_nop 0
	v_add_f32_dpp v2, v118, v118 row_mirror row_mask:0xf bank_mask:0xf bound_ctrl:1
	v_add_f32_dpp v118, v118, v118 row_mirror row_mask:0xf bank_mask:0xf bound_ctrl:1
	ds_read2st64_b64 v[100:103], v88 offset0:72 offset1:73
	s_waitcnt lgkmcnt(4)
	v_permlane16_swap_b32_e32 v118, v2
	v_add_f32_e32 v118, v118, v2
	v_pk_fma_f32 v[52:53], v[106:107], v[118:119], v[54:55] op_sel_hi:[1,0,1]
	v_pk_mul_f32 v[0:1], v[52:53], v[4:5] op_sel_hi:[0,1]
	v_pk_fma_f32 v[0:1], v[52:53], v[6:7], v[0:1] op_sel:[1,0,0]
	v_pk_mul_f32 v[10:11], v[108:109], v[10:11] op_sel_hi:[0,1]
	ds_read_b128 v[4:7], v90 offset:0x5400
	v_add_f32_dpp v0, v0, v0 quad_perm:[1,0,3,2] row_mask:0xf bank_mask:0xf bound_ctrl:1
	v_add_f32_dpp v1, v1, v1 quad_perm:[1,0,3,2] row_mask:0xf bank_mask:0xf bound_ctrl:1
	v_pk_fma_f32 v[54:55], v[52:53], v[8:9], v[10:11]
	v_add_f32_dpp v0, v0, v0 quad_perm:[2,3,0,1] row_mask:0xf bank_mask:0xf bound_ctrl:1
	ds_read_b128 v[8:11], v90 offset:0x1400
	s_nop 0
	v_add_f32_dpp v0, v0, v0 row_half_mirror row_mask:0xf bank_mask:0xf bound_ctrl:1
	v_add_u32_e32 v93, 0x480, v93
	s_nop 0
	v_add_f32_dpp v2, v0, v0 row_mirror row_mask:0xf bank_mask:0xf bound_ctrl:1
	v_add_f32_dpp v0, v0, v0 row_mirror row_mask:0xf bank_mask:0xf bound_ctrl:1
	ds_read2st64_b32 v[110:111], v89 offset0:202 offset1:203
	s_waitcnt lgkmcnt(3)
	v_permlane16_swap_b32_e32 v0, v2
	v_add_f32_e32 v0, v0, v2
	v_pk_fma_f32 v[52:53], v[100:101], v[0:1], v[54:55] op_sel_hi:[1,0,1]
	v_pk_mul_f32 v[118:119], v[52:53], v[112:113] op_sel_hi:[0,1]
	v_pk_fma_f32 v[118:119], v[52:53], v[114:115], v[118:119] op_sel:[1,0,0]
	v_pk_mul_f32 v[98:99], v[108:109], v[98:99] op_sel:[1,0]
	ds_read_b128 v[112:115], v90 offset:0x5600
	v_add_f32_dpp v118, v118, v118 quad_perm:[1,0,3,2] row_mask:0xf bank_mask:0xf bound_ctrl:1
	v_add_f32_dpp v119, v119, v119 quad_perm:[1,0,3,2] row_mask:0xf bank_mask:0xf bound_ctrl:1
	v_pk_fma_f32 v[54:55], v[52:53], v[96:97], v[98:99]
	v_add_f32_dpp v118, v118, v118 quad_perm:[2,3,0,1] row_mask:0xf bank_mask:0xf bound_ctrl:1
	ds_read_b128 v[96:99], v90 offset:0x1600
	s_nop 0
	v_add_f32_dpp v118, v118, v118 row_half_mirror row_mask:0xf bank_mask:0xf bound_ctrl:1
	ds_write2_b32 v93, v1, v119 offset0:0 offset1:36
	s_nop 0
	v_add_f32_dpp v2, v118, v118 row_mirror row_mask:0xf bank_mask:0xf bound_ctrl:1
	v_add_f32_dpp v118, v118, v118 row_mirror row_mask:0xf bank_mask:0xf bound_ctrl:1
	ds_read2st64_b64 v[104:107], v88 offset0:74 offset1:75
	s_waitcnt lgkmcnt(4)
	v_permlane16_swap_b32_e32 v118, v2
	v_add_f32_e32 v118, v118, v2
	v_pk_fma_f32 v[52:53], v[102:103], v[118:119], v[54:55] op_sel_hi:[1,0,1]
	v_pk_mul_f32 v[0:1], v[52:53], v[4:5] op_sel_hi:[0,1]
	v_pk_fma_f32 v[0:1], v[52:53], v[6:7], v[0:1] op_sel:[1,0,0]
	v_pk_mul_f32 v[10:11], v[110:111], v[10:11] op_sel_hi:[0,1]
	ds_read_b128 v[4:7], v90 offset:0x5800
	v_add_f32_dpp v0, v0, v0 quad_perm:[1,0,3,2] row_mask:0xf bank_mask:0xf bound_ctrl:1
	v_add_f32_dpp v1, v1, v1 quad_perm:[1,0,3,2] row_mask:0xf bank_mask:0xf bound_ctrl:1
	v_pk_fma_f32 v[54:55], v[52:53], v[8:9], v[10:11]
	v_add_f32_dpp v0, v0, v0 quad_perm:[2,3,0,1] row_mask:0xf bank_mask:0xf bound_ctrl:1
	ds_read_b128 v[8:11], v90 offset:0x1800
	s_nop 0
	v_add_f32_dpp v0, v0, v0 row_half_mirror row_mask:0xf bank_mask:0xf bound_ctrl:1
	s_nop 0
	s_nop 0
	v_add_f32_dpp v2, v0, v0 row_mirror row_mask:0xf bank_mask:0xf bound_ctrl:1
	v_add_f32_dpp v0, v0, v0 row_mirror row_mask:0xf bank_mask:0xf bound_ctrl:1
	ds_read2st64_b32 v[108:109], v89 offset0:204 offset1:205
	s_waitcnt lgkmcnt(3)
	v_permlane16_swap_b32_e32 v0, v2
	v_add_f32_e32 v0, v0, v2
	v_pk_fma_f32 v[52:53], v[104:105], v[0:1], v[54:55] op_sel_hi:[1,0,1]
	v_pk_mul_f32 v[118:119], v[52:53], v[112:113] op_sel_hi:[0,1]
	v_pk_fma_f32 v[118:119], v[52:53], v[114:115], v[118:119] op_sel:[1,0,0]
	v_pk_mul_f32 v[98:99], v[110:111], v[98:99] op_sel:[1,0]
	ds_read_b128 v[112:115], v90 offset:0x5a00
	v_add_f32_dpp v118, v118, v118 quad_perm:[1,0,3,2] row_mask:0xf bank_mask:0xf bound_ctrl:1
	v_add_f32_dpp v119, v119, v119 quad_perm:[1,0,3,2] row_mask:0xf bank_mask:0xf bound_ctrl:1
	v_pk_fma_f32 v[54:55], v[52:53], v[96:97], v[98:99]
	v_add_f32_dpp v118, v118, v118 quad_perm:[2,3,0,1] row_mask:0xf bank_mask:0xf bound_ctrl:1
	ds_read_b128 v[96:99], v90 offset:0x1a00
	s_nop 0
	v_add_f32_dpp v118, v118, v118 row_half_mirror row_mask:0xf bank_mask:0xf bound_ctrl:1
	ds_write2_b32 v93, v1, v119 offset0:72 offset1:108
	s_nop 0
	v_add_f32_dpp v2, v118, v118 row_mirror row_mask:0xf bank_mask:0xf bound_ctrl:1
	v_add_f32_dpp v118, v118, v118 row_mirror row_mask:0xf bank_mask:0xf bound_ctrl:1
	ds_read2st64_b64 v[100:103], v88 offset0:76 offset1:77
	s_waitcnt lgkmcnt(4)
	v_permlane16_swap_b32_e32 v118, v2
	v_add_f32_e32 v118, v118, v2
	v_pk_fma_f32 v[52:53], v[106:107], v[118:119], v[54:55] op_sel_hi:[1,0,1]
	v_pk_mul_f32 v[0:1], v[52:53], v[4:5] op_sel_hi:[0,1]
	v_pk_fma_f32 v[0:1], v[52:53], v[6:7], v[0:1] op_sel:[1,0,0]
	v_pk_mul_f32 v[10:11], v[108:109], v[10:11] op_sel_hi:[0,1]
	ds_read_b128 v[4:7], v90 offset:0x5c00
	v_add_f32_dpp v0, v0, v0 quad_perm:[1,0,3,2] row_mask:0xf bank_mask:0xf bound_ctrl:1
	v_add_f32_dpp v1, v1, v1 quad_perm:[1,0,3,2] row_mask:0xf bank_mask:0xf bound_ctrl:1
	v_pk_fma_f32 v[54:55], v[52:53], v[8:9], v[10:11]
	v_add_f32_dpp v0, v0, v0 quad_perm:[2,3,0,1] row_mask:0xf bank_mask:0xf bound_ctrl:1
	ds_read_b128 v[8:11], v90 offset:0x1c00
	s_nop 0
	v_add_f32_dpp v0, v0, v0 row_half_mirror row_mask:0xf bank_mask:0xf bound_ctrl:1
	s_nop 0
	s_nop 0
	v_add_f32_dpp v2, v0, v0 row_mirror row_mask:0xf bank_mask:0xf bound_ctrl:1
	v_add_f32_dpp v0, v0, v0 row_mirror row_mask:0xf bank_mask:0xf bound_ctrl:1
	ds_read2st64_b32 v[110:111], v89 offset0:206 offset1:207
	s_waitcnt lgkmcnt(3)
	v_permlane16_swap_b32_e32 v0, v2
	v_add_f32_e32 v0, v0, v2
	v_pk_fma_f32 v[52:53], v[100:101], v[0:1], v[54:55] op_sel_hi:[1,0,1]
	v_pk_mul_f32 v[118:119], v[52:53], v[112:113] op_sel_hi:[0,1]
	v_pk_fma_f32 v[118:119], v[52:53], v[114:115], v[118:119] op_sel:[1,0,0]
	v_pk_mul_f32 v[98:99], v[108:109], v[98:99] op_sel:[1,0]
	ds_read_b128 v[112:115], v90 offset:0x5e00
	v_add_f32_dpp v118, v118, v118 quad_perm:[1,0,3,2] row_mask:0xf bank_mask:0xf bound_ctrl:1
	v_add_f32_dpp v119, v119, v119 quad_perm:[1,0,3,2] row_mask:0xf bank_mask:0xf bound_ctrl:1
	v_pk_fma_f32 v[54:55], v[52:53], v[96:97], v[98:99]
	v_add_f32_dpp v118, v118, v118 quad_perm:[2,3,0,1] row_mask:0xf bank_mask:0xf bound_ctrl:1
	ds_read_b128 v[96:99], v90 offset:0x1e00
	s_nop 0
	v_add_f32_dpp v118, v118, v118 row_half_mirror row_mask:0xf bank_mask:0xf bound_ctrl:1
	ds_write2_b32 v93, v1, v119 offset0:144 offset1:180
	s_nop 0
	v_add_f32_dpp v2, v118, v118 row_mirror row_mask:0xf bank_mask:0xf bound_ctrl:1
	v_add_f32_dpp v118, v118, v118 row_mirror row_mask:0xf bank_mask:0xf bound_ctrl:1
	ds_read2st64_b64 v[104:107], v88 offset0:78 offset1:79
	s_waitcnt lgkmcnt(4)
	v_permlane16_swap_b32_e32 v118, v2
	v_add_f32_e32 v118, v118, v2
	v_pk_fma_f32 v[52:53], v[102:103], v[118:119], v[54:55] op_sel_hi:[1,0,1]
	v_pk_mul_f32 v[0:1], v[52:53], v[4:5] op_sel_hi:[0,1]
	v_pk_fma_f32 v[0:1], v[52:53], v[6:7], v[0:1] op_sel:[1,0,0]
	v_pk_mul_f32 v[10:11], v[110:111], v[10:11] op_sel_hi:[0,1]
	ds_read_b128 v[4:7], v90 offset:0x6000
	v_add_f32_dpp v0, v0, v0 quad_perm:[1,0,3,2] row_mask:0xf bank_mask:0xf bound_ctrl:1
	v_add_f32_dpp v1, v1, v1 quad_perm:[1,0,3,2] row_mask:0xf bank_mask:0xf bound_ctrl:1
	v_pk_fma_f32 v[54:55], v[52:53], v[8:9], v[10:11]
	v_add_f32_dpp v0, v0, v0 quad_perm:[2,3,0,1] row_mask:0xf bank_mask:0xf bound_ctrl:1
	ds_read_b128 v[8:11], v90 offset:0x2000
	s_nop 0
	v_add_f32_dpp v0, v0, v0 row_half_mirror row_mask:0xf bank_mask:0xf bound_ctrl:1
	s_nop 0
	s_nop 0
	v_add_f32_dpp v2, v0, v0 row_mirror row_mask:0xf bank_mask:0xf bound_ctrl:1
	v_add_f32_dpp v0, v0, v0 row_mirror row_mask:0xf bank_mask:0xf bound_ctrl:1
	ds_read2st64_b32 v[108:109], v89 offset0:208 offset1:209
	s_waitcnt lgkmcnt(3)
	v_permlane16_swap_b32_e32 v0, v2
	v_add_f32_e32 v0, v0, v2
	v_pk_fma_f32 v[52:53], v[104:105], v[0:1], v[54:55] op_sel_hi:[1,0,1]
	v_pk_mul_f32 v[118:119], v[52:53], v[112:113] op_sel_hi:[0,1]
	v_pk_fma_f32 v[118:119], v[52:53], v[114:115], v[118:119] op_sel:[1,0,0]
	v_pk_mul_f32 v[98:99], v[110:111], v[98:99] op_sel:[1,0]
	ds_read_b128 v[112:115], v90 offset:0x6200
	v_add_f32_dpp v118, v118, v118 quad_perm:[1,0,3,2] row_mask:0xf bank_mask:0xf bound_ctrl:1
	v_add_f32_dpp v119, v119, v119 quad_perm:[1,0,3,2] row_mask:0xf bank_mask:0xf bound_ctrl:1
	v_pk_fma_f32 v[54:55], v[52:53], v[96:97], v[98:99]
	v_add_f32_dpp v118, v118, v118 quad_perm:[2,3,0,1] row_mask:0xf bank_mask:0xf bound_ctrl:1
	ds_read_b128 v[96:99], v90 offset:0x2200
	s_nop 0
	v_add_f32_dpp v118, v118, v118 row_half_mirror row_mask:0xf bank_mask:0xf bound_ctrl:1
	ds_write2_b32 v93, v1, v119 offset0:216 offset1:252
	s_nop 0
	v_add_f32_dpp v2, v118, v118 row_mirror row_mask:0xf bank_mask:0xf bound_ctrl:1
	v_add_f32_dpp v118, v118, v118 row_mirror row_mask:0xf bank_mask:0xf bound_ctrl:1
	ds_read2st64_b64 v[100:103], v88 offset0:80 offset1:81
	s_waitcnt lgkmcnt(4)
	v_permlane16_swap_b32_e32 v118, v2
	v_add_f32_e32 v118, v118, v2
	v_pk_fma_f32 v[52:53], v[106:107], v[118:119], v[54:55] op_sel_hi:[1,0,1]
	s_cmp_eq_u32 s88, 0x800000
	s_cbranch_scc1 .LBB0_684
	v_pk_mul_f32 v[0:1], v[52:53], v[4:5] op_sel_hi:[0,1]
	v_pk_fma_f32 v[0:1], v[52:53], v[6:7], v[0:1] op_sel:[1,0,0]
	v_pk_mul_f32 v[10:11], v[108:109], v[10:11] op_sel_hi:[0,1]
	ds_read_b128 v[4:7], v90 offset:0x6400
	v_add_f32_dpp v0, v0, v0 quad_perm:[1,0,3,2] row_mask:0xf bank_mask:0xf bound_ctrl:1
	v_add_f32_dpp v1, v1, v1 quad_perm:[1,0,3,2] row_mask:0xf bank_mask:0xf bound_ctrl:1
	v_pk_fma_f32 v[54:55], v[52:53], v[8:9], v[10:11]
	v_add_f32_dpp v0, v0, v0 quad_perm:[2,3,0,1] row_mask:0xf bank_mask:0xf bound_ctrl:1
	ds_read_b128 v[8:11], v90 offset:0x2400
	s_nop 0
	v_add_f32_dpp v0, v0, v0 row_half_mirror row_mask:0xf bank_mask:0xf bound_ctrl:1
	v_add_u32_e32 v93, 0x480, v93
	s_nop 0
	v_add_f32_dpp v2, v0, v0 row_mirror row_mask:0xf bank_mask:0xf bound_ctrl:1
	v_add_f32_dpp v0, v0, v0 row_mirror row_mask:0xf bank_mask:0xf bound_ctrl:1
	ds_read2st64_b32 v[110:111], v89 offset0:210 offset1:211
	s_waitcnt lgkmcnt(3)
	v_permlane16_swap_b32_e32 v0, v2
	v_add_f32_e32 v0, v0, v2
	v_pk_fma_f32 v[52:53], v[100:101], v[0:1], v[54:55] op_sel_hi:[1,0,1]
	v_pk_mul_f32 v[118:119], v[52:53], v[112:113] op_sel_hi:[0,1]
	v_pk_fma_f32 v[118:119], v[52:53], v[114:115], v[118:119] op_sel:[1,0,0]
	v_pk_mul_f32 v[98:99], v[108:109], v[98:99] op_sel:[1,0]
	ds_read_b128 v[112:115], v90 offset:0x6600
	v_add_f32_dpp v118, v118, v118 quad_perm:[1,0,3,2] row_mask:0xf bank_mask:0xf bound_ctrl:1
	v_add_f32_dpp v119, v119, v119 quad_perm:[1,0,3,2] row_mask:0xf bank_mask:0xf bound_ctrl:1
	v_pk_fma_f32 v[54:55], v[52:53], v[96:97], v[98:99]
	v_add_f32_dpp v118, v118, v118 quad_perm:[2,3,0,1] row_mask:0xf bank_mask:0xf bound_ctrl:1
	ds_read_b128 v[96:99], v90 offset:0x2600
	s_nop 0
	v_add_f32_dpp v118, v118, v118 row_half_mirror row_mask:0xf bank_mask:0xf bound_ctrl:1
	ds_write2_b32 v93, v1, v119 offset0:0 offset1:36
	s_nop 0
	v_add_f32_dpp v2, v118, v118 row_mirror row_mask:0xf bank_mask:0xf bound_ctrl:1
	v_add_f32_dpp v118, v118, v118 row_mirror row_mask:0xf bank_mask:0xf bound_ctrl:1
	ds_read2st64_b64 v[104:107], v88 offset0:82 offset1:83
	s_waitcnt lgkmcnt(4)
	v_permlane16_swap_b32_e32 v118, v2
	v_add_f32_e32 v118, v118, v2
	v_pk_fma_f32 v[52:53], v[102:103], v[118:119], v[54:55] op_sel_hi:[1,0,1]
	v_pk_mul_f32 v[0:1], v[52:53], v[4:5] op_sel_hi:[0,1]
	v_pk_fma_f32 v[0:1], v[52:53], v[6:7], v[0:1] op_sel:[1,0,0]
	v_pk_mul_f32 v[10:11], v[110:111], v[10:11] op_sel_hi:[0,1]
	ds_read_b128 v[4:7], v90 offset:0x6800
	v_add_f32_dpp v0, v0, v0 quad_perm:[1,0,3,2] row_mask:0xf bank_mask:0xf bound_ctrl:1
	v_add_f32_dpp v1, v1, v1 quad_perm:[1,0,3,2] row_mask:0xf bank_mask:0xf bound_ctrl:1
	v_pk_fma_f32 v[54:55], v[52:53], v[8:9], v[10:11]
	v_add_f32_dpp v0, v0, v0 quad_perm:[2,3,0,1] row_mask:0xf bank_mask:0xf bound_ctrl:1
	ds_read_b128 v[8:11], v90 offset:0x2800
	s_nop 0
	v_add_f32_dpp v0, v0, v0 row_half_mirror row_mask:0xf bank_mask:0xf bound_ctrl:1
	s_nop 0
	s_nop 0
	v_add_f32_dpp v2, v0, v0 row_mirror row_mask:0xf bank_mask:0xf bound_ctrl:1
	v_add_f32_dpp v0, v0, v0 row_mirror row_mask:0xf bank_mask:0xf bound_ctrl:1
	ds_read2st64_b32 v[108:109], v89 offset0:212 offset1:213
	s_waitcnt lgkmcnt(3)
	v_permlane16_swap_b32_e32 v0, v2
	v_add_f32_e32 v0, v0, v2
	v_pk_fma_f32 v[52:53], v[104:105], v[0:1], v[54:55] op_sel_hi:[1,0,1]
	v_pk_mul_f32 v[118:119], v[52:53], v[112:113] op_sel_hi:[0,1]
	v_pk_fma_f32 v[118:119], v[52:53], v[114:115], v[118:119] op_sel:[1,0,0]
	v_pk_mul_f32 v[98:99], v[110:111], v[98:99] op_sel:[1,0]
	ds_read_b128 v[112:115], v90 offset:0x6a00
	v_add_f32_dpp v118, v118, v118 quad_perm:[1,0,3,2] row_mask:0xf bank_mask:0xf bound_ctrl:1
	v_add_f32_dpp v119, v119, v119 quad_perm:[1,0,3,2] row_mask:0xf bank_mask:0xf bound_ctrl:1
	v_pk_fma_f32 v[54:55], v[52:53], v[96:97], v[98:99]
	v_add_f32_dpp v118, v118, v118 quad_perm:[2,3,0,1] row_mask:0xf bank_mask:0xf bound_ctrl:1
	ds_read_b128 v[96:99], v90 offset:0x2a00
	s_nop 0
	v_add_f32_dpp v118, v118, v118 row_half_mirror row_mask:0xf bank_mask:0xf bound_ctrl:1
	ds_write2_b32 v93, v1, v119 offset0:72 offset1:108
	s_nop 0
	v_add_f32_dpp v2, v118, v118 row_mirror row_mask:0xf bank_mask:0xf bound_ctrl:1
	v_add_f32_dpp v118, v118, v118 row_mirror row_mask:0xf bank_mask:0xf bound_ctrl:1
	ds_read2st64_b64 v[100:103], v88 offset0:84 offset1:85
	s_waitcnt lgkmcnt(4)
	v_permlane16_swap_b32_e32 v118, v2
	v_add_f32_e32 v118, v118, v2
	v_pk_fma_f32 v[52:53], v[106:107], v[118:119], v[54:55] op_sel_hi:[1,0,1]
	v_pk_mul_f32 v[0:1], v[52:53], v[4:5] op_sel_hi:[0,1]
	v_pk_fma_f32 v[0:1], v[52:53], v[6:7], v[0:1] op_sel:[1,0,0]
	v_pk_mul_f32 v[10:11], v[108:109], v[10:11] op_sel_hi:[0,1]
	ds_read_b128 v[4:7], v90 offset:0x6c00
	v_add_f32_dpp v0, v0, v0 quad_perm:[1,0,3,2] row_mask:0xf bank_mask:0xf bound_ctrl:1
	v_add_f32_dpp v1, v1, v1 quad_perm:[1,0,3,2] row_mask:0xf bank_mask:0xf bound_ctrl:1
	v_pk_fma_f32 v[54:55], v[52:53], v[8:9], v[10:11]
	v_add_f32_dpp v0, v0, v0 quad_perm:[2,3,0,1] row_mask:0xf bank_mask:0xf bound_ctrl:1
	ds_read_b128 v[8:11], v90 offset:0x2c00
	s_nop 0
	v_add_f32_dpp v0, v0, v0 row_half_mirror row_mask:0xf bank_mask:0xf bound_ctrl:1
	s_nop 0
	s_nop 0
	v_add_f32_dpp v2, v0, v0 row_mirror row_mask:0xf bank_mask:0xf bound_ctrl:1
	v_add_f32_dpp v0, v0, v0 row_mirror row_mask:0xf bank_mask:0xf bound_ctrl:1
	ds_read2st64_b32 v[110:111], v89 offset0:214 offset1:215
	s_waitcnt lgkmcnt(3)
	v_permlane16_swap_b32_e32 v0, v2
	v_add_f32_e32 v0, v0, v2
	v_pk_fma_f32 v[52:53], v[100:101], v[0:1], v[54:55] op_sel_hi:[1,0,1]
	v_pk_mul_f32 v[118:119], v[52:53], v[112:113] op_sel_hi:[0,1]
	v_pk_fma_f32 v[118:119], v[52:53], v[114:115], v[118:119] op_sel:[1,0,0]
	v_pk_mul_f32 v[98:99], v[108:109], v[98:99] op_sel:[1,0]
	ds_read_b128 v[112:115], v90 offset:0x6e00
	v_add_f32_dpp v118, v118, v118 quad_perm:[1,0,3,2] row_mask:0xf bank_mask:0xf bound_ctrl:1
	v_add_f32_dpp v119, v119, v119 quad_perm:[1,0,3,2] row_mask:0xf bank_mask:0xf bound_ctrl:1
	v_pk_fma_f32 v[54:55], v[52:53], v[96:97], v[98:99]
	v_add_f32_dpp v118, v118, v118 quad_perm:[2,3,0,1] row_mask:0xf bank_mask:0xf bound_ctrl:1
	ds_read_b128 v[96:99], v90 offset:0x2e00
	s_nop 0
	v_add_f32_dpp v118, v118, v118 row_half_mirror row_mask:0xf bank_mask:0xf bound_ctrl:1
	ds_write2_b32 v93, v1, v119 offset0:144 offset1:180
	s_nop 0
	v_add_f32_dpp v2, v118, v118 row_mirror row_mask:0xf bank_mask:0xf bound_ctrl:1
	v_add_f32_dpp v118, v118, v118 row_mirror row_mask:0xf bank_mask:0xf bound_ctrl:1
	ds_read2st64_b64 v[104:107], v88 offset0:86 offset1:87
	s_waitcnt lgkmcnt(4)
	v_permlane16_swap_b32_e32 v118, v2
	v_add_f32_e32 v118, v118, v2
	v_pk_fma_f32 v[52:53], v[102:103], v[118:119], v[54:55] op_sel_hi:[1,0,1]
	v_pk_mul_f32 v[0:1], v[52:53], v[4:5] op_sel_hi:[0,1]
	v_pk_fma_f32 v[0:1], v[52:53], v[6:7], v[0:1] op_sel:[1,0,0]
	v_pk_mul_f32 v[10:11], v[110:111], v[10:11] op_sel_hi:[0,1]
	ds_read_b128 v[4:7], v90 offset:0x7000
	v_add_f32_dpp v0, v0, v0 quad_perm:[1,0,3,2] row_mask:0xf bank_mask:0xf bound_ctrl:1
	v_add_f32_dpp v1, v1, v1 quad_perm:[1,0,3,2] row_mask:0xf bank_mask:0xf bound_ctrl:1
	v_pk_fma_f32 v[54:55], v[52:53], v[8:9], v[10:11]
	v_add_f32_dpp v0, v0, v0 quad_perm:[2,3,0,1] row_mask:0xf bank_mask:0xf bound_ctrl:1
	ds_read_b128 v[8:11], v90 offset:0x3000
	s_nop 0
	v_add_f32_dpp v0, v0, v0 row_half_mirror row_mask:0xf bank_mask:0xf bound_ctrl:1
	s_nop 0
	s_nop 0
	v_add_f32_dpp v2, v0, v0 row_mirror row_mask:0xf bank_mask:0xf bound_ctrl:1
	v_add_f32_dpp v0, v0, v0 row_mirror row_mask:0xf bank_mask:0xf bound_ctrl:1
	ds_read2st64_b32 v[108:109], v89 offset0:216 offset1:217
	s_waitcnt lgkmcnt(3)
	v_permlane16_swap_b32_e32 v0, v2
	v_add_f32_e32 v0, v0, v2
	v_pk_fma_f32 v[52:53], v[104:105], v[0:1], v[54:55] op_sel_hi:[1,0,1]
	v_pk_mul_f32 v[118:119], v[52:53], v[112:113] op_sel_hi:[0,1]
	v_pk_fma_f32 v[118:119], v[52:53], v[114:115], v[118:119] op_sel:[1,0,0]
	v_pk_mul_f32 v[98:99], v[110:111], v[98:99] op_sel:[1,0]
	ds_read_b128 v[112:115], v90 offset:0x7200
	v_add_f32_dpp v118, v118, v118 quad_perm:[1,0,3,2] row_mask:0xf bank_mask:0xf bound_ctrl:1
	v_add_f32_dpp v119, v119, v119 quad_perm:[1,0,3,2] row_mask:0xf bank_mask:0xf bound_ctrl:1
	v_pk_fma_f32 v[54:55], v[52:53], v[96:97], v[98:99]
	v_add_f32_dpp v118, v118, v118 quad_perm:[2,3,0,1] row_mask:0xf bank_mask:0xf bound_ctrl:1
	ds_read_b128 v[96:99], v90 offset:0x3200
	s_nop 0
	v_add_f32_dpp v118, v118, v118 row_half_mirror row_mask:0xf bank_mask:0xf bound_ctrl:1
	ds_write2_b32 v93, v1, v119 offset0:216 offset1:252
	s_nop 0
	v_add_f32_dpp v2, v118, v118 row_mirror row_mask:0xf bank_mask:0xf bound_ctrl:1
	v_add_f32_dpp v118, v118, v118 row_mirror row_mask:0xf bank_mask:0xf bound_ctrl:1
	ds_read2st64_b64 v[100:103], v88 offset0:88 offset1:89
	s_waitcnt lgkmcnt(4)
	v_permlane16_swap_b32_e32 v118, v2
	v_add_f32_e32 v118, v118, v2
	v_pk_fma_f32 v[52:53], v[106:107], v[118:119], v[54:55] op_sel_hi:[1,0,1]
	v_pk_mul_f32 v[0:1], v[52:53], v[4:5] op_sel_hi:[0,1]
	v_pk_fma_f32 v[0:1], v[52:53], v[6:7], v[0:1] op_sel:[1,0,0]
	v_pk_mul_f32 v[10:11], v[108:109], v[10:11] op_sel_hi:[0,1]
	ds_read_b128 v[4:7], v90 offset:0x7400
	v_add_f32_dpp v0, v0, v0 quad_perm:[1,0,3,2] row_mask:0xf bank_mask:0xf bound_ctrl:1
	v_add_f32_dpp v1, v1, v1 quad_perm:[1,0,3,2] row_mask:0xf bank_mask:0xf bound_ctrl:1
	v_pk_fma_f32 v[54:55], v[52:53], v[8:9], v[10:11]
	v_add_f32_dpp v0, v0, v0 quad_perm:[2,3,0,1] row_mask:0xf bank_mask:0xf bound_ctrl:1
	ds_read_b128 v[8:11], v90 offset:0x3400
	s_nop 0
	v_add_f32_dpp v0, v0, v0 row_half_mirror row_mask:0xf bank_mask:0xf bound_ctrl:1
	v_add_u32_e32 v93, 0x480, v93
	s_nop 0
	v_add_f32_dpp v2, v0, v0 row_mirror row_mask:0xf bank_mask:0xf bound_ctrl:1
	v_add_f32_dpp v0, v0, v0 row_mirror row_mask:0xf bank_mask:0xf bound_ctrl:1
	ds_read2st64_b32 v[110:111], v89 offset0:218 offset1:219
	s_waitcnt lgkmcnt(3)
	v_permlane16_swap_b32_e32 v0, v2
	v_add_f32_e32 v0, v0, v2
	v_pk_fma_f32 v[52:53], v[100:101], v[0:1], v[54:55] op_sel_hi:[1,0,1]
	v_pk_mul_f32 v[118:119], v[52:53], v[112:113] op_sel_hi:[0,1]
	v_pk_fma_f32 v[118:119], v[52:53], v[114:115], v[118:119] op_sel:[1,0,0]
	v_pk_mul_f32 v[98:99], v[108:109], v[98:99] op_sel:[1,0]
	ds_read_b128 v[112:115], v90 offset:0x7600
	v_add_f32_dpp v118, v118, v118 quad_perm:[1,0,3,2] row_mask:0xf bank_mask:0xf bound_ctrl:1
	v_add_f32_dpp v119, v119, v119 quad_perm:[1,0,3,2] row_mask:0xf bank_mask:0xf bound_ctrl:1
	v_pk_fma_f32 v[54:55], v[52:53], v[96:97], v[98:99]
	v_add_f32_dpp v118, v118, v118 quad_perm:[2,3,0,1] row_mask:0xf bank_mask:0xf bound_ctrl:1
	ds_read_b128 v[96:99], v90 offset:0x3600
	s_nop 0
	v_add_f32_dpp v118, v118, v118 row_half_mirror row_mask:0xf bank_mask:0xf bound_ctrl:1
	ds_write2_b32 v93, v1, v119 offset0:0 offset1:36
	s_nop 0
	v_add_f32_dpp v2, v118, v118 row_mirror row_mask:0xf bank_mask:0xf bound_ctrl:1
	v_add_f32_dpp v118, v118, v118 row_mirror row_mask:0xf bank_mask:0xf bound_ctrl:1
	ds_read2st64_b64 v[104:107], v88 offset0:90 offset1:91
	s_waitcnt lgkmcnt(4)
	v_permlane16_swap_b32_e32 v118, v2
	v_add_f32_e32 v118, v118, v2
	v_pk_fma_f32 v[52:53], v[102:103], v[118:119], v[54:55] op_sel_hi:[1,0,1]
	v_pk_mul_f32 v[0:1], v[52:53], v[4:5] op_sel_hi:[0,1]
	v_pk_fma_f32 v[0:1], v[52:53], v[6:7], v[0:1] op_sel:[1,0,0]
	v_pk_mul_f32 v[10:11], v[110:111], v[10:11] op_sel_hi:[0,1]
	ds_read_b128 v[4:7], v90 offset:0x7800
	v_add_f32_dpp v0, v0, v0 quad_perm:[1,0,3,2] row_mask:0xf bank_mask:0xf bound_ctrl:1
	v_add_f32_dpp v1, v1, v1 quad_perm:[1,0,3,2] row_mask:0xf bank_mask:0xf bound_ctrl:1
	v_pk_fma_f32 v[54:55], v[52:53], v[8:9], v[10:11]
	v_add_f32_dpp v0, v0, v0 quad_perm:[2,3,0,1] row_mask:0xf bank_mask:0xf bound_ctrl:1
	ds_read_b128 v[8:11], v90 offset:0x3800
	s_nop 0
	v_add_f32_dpp v0, v0, v0 row_half_mirror row_mask:0xf bank_mask:0xf bound_ctrl:1
	s_nop 0
	s_nop 0
	v_add_f32_dpp v2, v0, v0 row_mirror row_mask:0xf bank_mask:0xf bound_ctrl:1
	v_add_f32_dpp v0, v0, v0 row_mirror row_mask:0xf bank_mask:0xf bound_ctrl:1
	ds_read2st64_b32 v[108:109], v89 offset0:220 offset1:221
	s_waitcnt lgkmcnt(3)
	v_permlane16_swap_b32_e32 v0, v2
	v_add_f32_e32 v0, v0, v2
	v_pk_fma_f32 v[52:53], v[104:105], v[0:1], v[54:55] op_sel_hi:[1,0,1]
	v_pk_mul_f32 v[118:119], v[52:53], v[112:113] op_sel_hi:[0,1]
	v_pk_fma_f32 v[118:119], v[52:53], v[114:115], v[118:119] op_sel:[1,0,0]
	v_pk_mul_f32 v[98:99], v[110:111], v[98:99] op_sel:[1,0]
	ds_read_b128 v[112:115], v90 offset:0x7a00
	v_add_f32_dpp v118, v118, v118 quad_perm:[1,0,3,2] row_mask:0xf bank_mask:0xf bound_ctrl:1
	v_add_f32_dpp v119, v119, v119 quad_perm:[1,0,3,2] row_mask:0xf bank_mask:0xf bound_ctrl:1
	v_pk_fma_f32 v[54:55], v[52:53], v[96:97], v[98:99]
	v_add_f32_dpp v118, v118, v118 quad_perm:[2,3,0,1] row_mask:0xf bank_mask:0xf bound_ctrl:1
	ds_read_b128 v[96:99], v90 offset:0x3a00
	s_nop 0
	v_add_f32_dpp v118, v118, v118 row_half_mirror row_mask:0xf bank_mask:0xf bound_ctrl:1
	ds_write2_b32 v93, v1, v119 offset0:72 offset1:108
	s_nop 0
	v_add_f32_dpp v2, v118, v118 row_mirror row_mask:0xf bank_mask:0xf bound_ctrl:1
	v_add_f32_dpp v118, v118, v118 row_mirror row_mask:0xf bank_mask:0xf bound_ctrl:1
	ds_read2st64_b64 v[100:103], v88 offset0:92 offset1:93
	s_waitcnt lgkmcnt(4)
	v_permlane16_swap_b32_e32 v118, v2
	v_add_f32_e32 v118, v118, v2
	v_pk_fma_f32 v[52:53], v[106:107], v[118:119], v[54:55] op_sel_hi:[1,0,1]
	v_pk_mul_f32 v[0:1], v[52:53], v[4:5] op_sel_hi:[0,1]
	v_pk_fma_f32 v[0:1], v[52:53], v[6:7], v[0:1] op_sel:[1,0,0]
	v_pk_mul_f32 v[10:11], v[108:109], v[10:11] op_sel_hi:[0,1]
	ds_read_b128 v[4:7], v90 offset:0x7c00
	v_add_f32_dpp v0, v0, v0 quad_perm:[1,0,3,2] row_mask:0xf bank_mask:0xf bound_ctrl:1
	v_add_f32_dpp v1, v1, v1 quad_perm:[1,0,3,2] row_mask:0xf bank_mask:0xf bound_ctrl:1
	v_pk_fma_f32 v[54:55], v[52:53], v[8:9], v[10:11]
	v_add_f32_dpp v0, v0, v0 quad_perm:[2,3,0,1] row_mask:0xf bank_mask:0xf bound_ctrl:1
	ds_read_b128 v[8:11], v90 offset:0x3c00
	s_nop 0
	v_add_f32_dpp v0, v0, v0 row_half_mirror row_mask:0xf bank_mask:0xf bound_ctrl:1
	s_nop 0
	s_nop 0
	v_add_f32_dpp v2, v0, v0 row_mirror row_mask:0xf bank_mask:0xf bound_ctrl:1
	v_add_f32_dpp v0, v0, v0 row_mirror row_mask:0xf bank_mask:0xf bound_ctrl:1
	ds_read2st64_b32 v[110:111], v89 offset0:222 offset1:223
	s_waitcnt lgkmcnt(3)
	v_permlane16_swap_b32_e32 v0, v2
	v_add_f32_e32 v0, v0, v2
	v_pk_fma_f32 v[52:53], v[100:101], v[0:1], v[54:55] op_sel_hi:[1,0,1]
	v_pk_mul_f32 v[118:119], v[52:53], v[112:113] op_sel_hi:[0,1]
	v_pk_fma_f32 v[118:119], v[52:53], v[114:115], v[118:119] op_sel:[1,0,0]
	v_pk_mul_f32 v[98:99], v[108:109], v[98:99] op_sel:[1,0]
	ds_read_b128 v[112:115], v90 offset:0x7e00
	v_add_f32_dpp v118, v118, v118 quad_perm:[1,0,3,2] row_mask:0xf bank_mask:0xf bound_ctrl:1
	v_add_f32_dpp v119, v119, v119 quad_perm:[1,0,3,2] row_mask:0xf bank_mask:0xf bound_ctrl:1
	v_pk_fma_f32 v[54:55], v[52:53], v[96:97], v[98:99]
	v_add_f32_dpp v118, v118, v118 quad_perm:[2,3,0,1] row_mask:0xf bank_mask:0xf bound_ctrl:1
	ds_read_b128 v[96:99], v90 offset:0x3e00
	s_nop 0
	v_add_f32_dpp v118, v118, v118 row_half_mirror row_mask:0xf bank_mask:0xf bound_ctrl:1
	ds_write2_b32 v93, v1, v119 offset0:144 offset1:180
	s_nop 0
	v_add_f32_dpp v2, v118, v118 row_mirror row_mask:0xf bank_mask:0xf bound_ctrl:1
	v_add_f32_dpp v118, v118, v118 row_mirror row_mask:0xf bank_mask:0xf bound_ctrl:1
	ds_read2st64_b64 v[104:107], v88 offset0:94 offset1:95
	s_waitcnt lgkmcnt(4)
	v_permlane16_swap_b32_e32 v118, v2
	v_add_f32_e32 v118, v118, v2
	v_pk_fma_f32 v[52:53], v[102:103], v[118:119], v[54:55] op_sel_hi:[1,0,1]
	v_pk_mul_f32 v[0:1], v[52:53], v[4:5] op_sel_hi:[0,1]
	v_pk_fma_f32 v[0:1], v[52:53], v[6:7], v[0:1] op_sel:[1,0,0]
	v_pk_mul_f32 v[10:11], v[110:111], v[10:11] op_sel_hi:[0,1]
	s_nop 0
	v_add_f32_dpp v0, v0, v0 quad_perm:[1,0,3,2] row_mask:0xf bank_mask:0xf bound_ctrl:1
	v_add_f32_dpp v1, v1, v1 quad_perm:[1,0,3,2] row_mask:0xf bank_mask:0xf bound_ctrl:1
	v_pk_fma_f32 v[54:55], v[52:53], v[8:9], v[10:11]
	v_add_f32_dpp v0, v0, v0 quad_perm:[2,3,0,1] row_mask:0xf bank_mask:0xf bound_ctrl:1
	s_nop 0
	s_nop 0
	v_add_f32_dpp v0, v0, v0 row_half_mirror row_mask:0xf bank_mask:0xf bound_ctrl:1
	s_nop 0
	s_nop 0
	v_add_f32_dpp v2, v0, v0 row_mirror row_mask:0xf bank_mask:0xf bound_ctrl:1
	v_add_f32_dpp v0, v0, v0 row_mirror row_mask:0xf bank_mask:0xf bound_ctrl:1
	s_nop 0
	s_waitcnt lgkmcnt(0)
	v_permlane16_swap_b32_e32 v0, v2
	v_add_f32_e32 v0, v0, v2
	v_pk_fma_f32 v[52:53], v[104:105], v[0:1], v[54:55] op_sel_hi:[1,0,1]
	v_pk_mul_f32 v[118:119], v[52:53], v[112:113] op_sel_hi:[0,1]
	v_pk_fma_f32 v[118:119], v[52:53], v[114:115], v[118:119] op_sel:[1,0,0]
	v_pk_mul_f32 v[98:99], v[110:111], v[98:99] op_sel:[1,0]
	s_nop 0
	v_add_f32_dpp v118, v118, v118 quad_perm:[1,0,3,2] row_mask:0xf bank_mask:0xf bound_ctrl:1
	v_add_f32_dpp v119, v119, v119 quad_perm:[1,0,3,2] row_mask:0xf bank_mask:0xf bound_ctrl:1
	v_pk_fma_f32 v[54:55], v[52:53], v[96:97], v[98:99]
	v_add_f32_dpp v118, v118, v118 quad_perm:[2,3,0,1] row_mask:0xf bank_mask:0xf bound_ctrl:1
	s_nop 0
	s_nop 0
	v_add_f32_dpp v118, v118, v118 row_half_mirror row_mask:0xf bank_mask:0xf bound_ctrl:1
	ds_write2_b32 v93, v1, v119 offset0:216 offset1:252
	s_nop 0
	v_add_f32_dpp v2, v118, v118 row_mirror row_mask:0xf bank_mask:0xf bound_ctrl:1
	v_add_f32_dpp v118, v118, v118 row_mirror row_mask:0xf bank_mask:0xf bound_ctrl:1
	s_nop 0
	s_nop 0
	v_permlane16_swap_b32_e32 v118, v2
	v_add_f32_e32 v118, v118, v2
	v_pk_fma_f32 v[52:53], v[106:107], v[118:119], v[54:55] op_sel_hi:[1,0,1]
	ds_read_b128 v[120:123], v92
	ds_read_b128 v[124:127], v92 offset:16
	ds_read_b128 v[104:107], v92 offset:32
	ds_read_b128 v[116:119], v92 offset:48
	s_min_u32 s83, s31, 32
	v_cmp_gt_u32_e32 vcc, s83, v87
	s_cmp_lg_u32 s88, 0
	s_cselect_b64 s[8:9], -1, 0
	v_cmp_ne_u32_e64 s[6:7], 0, v87
	s_or_b64 s[6:7], s[6:7], s[8:9]
	s_and_b64 s[8:9], vcc, s[6:7]
	v_lshl_add_u64 v[0:1], v[50:51], 0, s[88:89]
	v_lshl_add_u64 v[0:1], v[94:95], 0, v[0:1]
	v_add_co_u32_e32 v0, vcc, 0x10698000, v0
	s_nop 1
	v_addc_co_u32_e32 v1, vcc, 0, v1, vcc
	s_barrier
	s_add_i32 s30, s30, 1
	s_add_u32 s88, s88, 0x10000
	s_addc_u32 s89, s89, 0
	s_sub_i32 s31, s31, 32
	s_bitcmp1_b32 s30, 0
	s_cselect_b32 s6, 0xe000, 0
	v_add_u32_e32 v90, s6, v58
	v_sub_u32_e32 v88, v90, v61
	v_add_u32_e32 v89, s6, v86
	ds_read_b128 v[4:7], v90 offset:0x4000
	ds_read_b128 v[8:11], v90 offset:0x0
	ds_read2st64_b32 v[108:109], v89 offset0:192 offset1:193
	ds_read2st64_b64 v[100:103], v88 offset0:64 offset1:65
	ds_read_b128 v[112:115], v90 offset:0x4200
	ds_read_b128 v[96:99], v90 offset:0x200
	v_mov_b32_e32 v93, v91
	s_waitcnt lgkmcnt(6)
	v_add_f32_e32 v120, v120, v121
	v_add_f32_e32 v122, v122, v123
	v_add_f32_e32 v124, v124, v125
	v_add_f32_e32 v126, v126, v127
	v_add_f32_e32 v104, v104, v105
	v_add_f32_e32 v106, v106, v107
	v_add_f32_e32 v116, v116, v117
	v_add_f32_e32 v118, v118, v119
	v_add_f32_e32 v120, v120, v122
	v_add_f32_e32 v124, v124, v126
	v_add_f32_e32 v104, v104, v106
	v_add_f32_e32 v116, v116, v118
	v_add_f32_e32 v120, v120, v124
	v_add_f32_e32 v104, v104, v116
	v_add_f32_e32 v120, v120, v104
	s_and_saveexec_b64 s[6:7], s[8:9]
	global_store_dword v[0:1], v120, off
	s_or_b64 exec, exec, s[6:7]
	s_waitcnt lgkmcnt(3)
	s_branch .Lrw_steps
.LBB0_684:
	s_waitcnt lgkmcnt(0)
	ds_read_b128 v[4:7], v92
	ds_read_b128 v[8:11], v92 offset:16
	ds_read_b128 v[96:99], v92 offset:32
	ds_read_b128 v[100:103], v92 offset:48
	s_min_u32 s83, s31, 32
	v_cmp_gt_u32_e32 vcc, s83, v87
	s_cmp_lg_u32 s88, 0
	s_cselect_b64 s[8:9], -1, 0
	v_cmp_ne_u32_e64 s[6:7], 0, v87
	s_or_b64 s[6:7], s[6:7], s[8:9]
	s_and_b64 s[8:9], vcc, s[6:7]
	v_lshl_add_u64 v[0:1], v[50:51], 0, s[88:89]
	v_lshl_add_u64 v[0:1], v[94:95], 0, v[0:1]
	v_add_co_u32_e32 v0, vcc, 0x10698000, v0
	s_nop 1
	v_addc_co_u32_e32 v1, vcc, 0, v1, vcc
	s_waitcnt lgkmcnt(0)
	v_add_f32_e32 v4, v4, v5
	v_add_f32_e32 v6, v6, v7
	v_add_f32_e32 v8, v8, v9
	v_add_f32_e32 v10, v10, v11
	v_add_f32_e32 v96, v96, v97
	v_add_f32_e32 v98, v98, v99
	v_add_f32_e32 v100, v100, v101
	v_add_f32_e32 v102, v102, v103
	v_add_f32_e32 v4, v4, v6
	v_add_f32_e32 v8, v8, v10
	v_add_f32_e32 v96, v96, v98
	v_add_f32_e32 v100, v100, v102
	v_add_f32_e32 v4, v4, v8
	v_add_f32_e32 v96, v96, v100
	v_add_f32_e32 v4, v4, v96
	s_and_saveexec_b64 s[6:7], s[8:9]
	global_store_dword v[0:1], v4, off
	s_or_b64 exec, exec, s[6:7]
	s_add_i32 s30, s30, 1
	s_barrier
	s_add_u32 s88, s88, 0x10000
	s_addc_u32 s89, s89, 0
	s_sub_i32 s31, s31, 32
